# position-DFT tile K-loop: fragments read up front, early buffer-release barrier, LDS-DMA issued two K-steps ahead
# speedup vs baseline: 1.1189x; 1.0061x over previous
; #define G_WAIT() { asm volatile("s_waitcnt vmcnt(0)" ::: "memory"); __syncthreads(); }
;     ...
;   const bf16_t* ag = A + (size_t)lrow * lda + lch * 8;
;   const bf16_t* bg = Bt + (size_t)lrow * ldb + lch * 8;
;   const size_t a32 = (size_t)32 * lda, b32 = (size_t)32 * ldb;
;   f32x16 acc[2][2];
; #pragma unroll
;   for (int i = 0; i < 2; ++i)
; #pragma unroll
;     for (int j = 0; j < 2; ++j)
; #pragma unroll
;       for (int e = 0; e < 16; ++e) acc[i][j][e] = 0.f;
;   const int nk = K >> 6;
;   const int rsw = (l31 >> 1) & 7;
;   const int aoff = (wr * 64 + l31) * 128, boff = 16384 + (wc * 64 + l31) * 128;
;   char* ldst = lds + tid * 16;
;     ...
;   G_DMA(0, 0);
;   G_WAIT();
;   for (int kt = 0; kt < nk; kt += 2) {
;     if (kt + 1 < nk) G_DMA(1, kt + 1);
.LBB0_167:
	v_mov_b32_e32 v82, v196
	v_mov_b32_e32 v7, v1
	v_bfe_u32 v0, v82, 3, 5
	v_lshrrev_b32_e32 v9, 4, v82
	v_xor_b32_e32 v6, v9, v82
	v_mul_u32_u24_e32 v0, s41, v0
	v_lshlrev_b32_e32 v0, 1, v0
	v_lshlrev_b32_e32 v6, 4, v6
	v_lshl_add_u64 v[2:3], s[20:21], 0, v[0:1]
	v_lshl_add_u64 v[4:5], s[18:19], 0, v[0:1]
	v_and_b32_e32 v6, 0x70, v6
	v_lshrrev_b32_e32 v8, 8, v82
	s_mov_b32 s2, 0x11000
	v_lshl_add_u64 v[4:5], v[4:5], 0, v[6:7]
	v_lshl_add_u64 v[2:3], v[2:3], 0, v[6:7]
	v_mov_b32_e32 v6, 4
	v_mad_i32_i24 v85, v8, s2, 0
	v_lshlrev_b32_sdwa v6, v6, v82 dst_sel:DWORD dst_unused:UNUSED_PAD src0_sel:DWORD src1_sel:BYTE_0
	v_add_u32_e32 v86, v85, v6
	v_add_u32_e32 v87, 0x4000, v86
	v_readfirstlane_b32 s2, v86
	s_mov_b32 m0, s2
	v_readfirstlane_b32 s2, v87
	v_add_u32_e32 v88, 0x1000, v86
	global_load_lds_dwordx4 v[4:5], off
	s_mov_b32 m0, s2
	s_lshl_b32 s2, s41, 6
	v_readfirstlane_b32 s5, v88
	v_add_u32_e32 v89, 0x5000, v86
	global_load_lds_dwordx4 v[2:3], off
	v_lshl_add_u64 v[4:5], v[4:5], 0, s[2:3]
	s_mov_b32 m0, s5
	v_readfirstlane_b32 s5, v89
	v_add_u32_e32 v90, 0x2000, v86
	global_load_lds_dwordx4 v[4:5], off
	v_lshl_add_u64 v[2:3], v[2:3], 0, s[2:3]
	s_mov_b32 m0, s5
	v_readfirstlane_b32 s5, v90
	v_add_u32_e32 v91, 0x6000, v86
	global_load_lds_dwordx4 v[2:3], off
	v_lshl_add_u64 v[4:5], v[4:5], 0, s[2:3]
	s_mov_b32 m0, s5
	v_readfirstlane_b32 s5, v91
	v_add_u32_e32 v92, 0x3000, v86
	global_load_lds_dwordx4 v[4:5], off
	v_lshl_add_u64 v[2:3], v[2:3], 0, s[2:3]
	s_mov_b32 m0, s5
	v_readfirstlane_b32 s5, v92
	v_add_u32_e32 v93, 0x7000, v86
	global_load_lds_dwordx4 v[2:3], off
	v_lshl_add_u64 v[4:5], v[4:5], 0, s[2:3]
	s_mov_b32 m0, s5
	v_readfirstlane_b32 s5, v93
	global_load_lds_dwordx4 v[4:5], off
	v_lshl_add_u64 v[2:3], v[2:3], 0, s[2:3]
	s_mov_b32 m0, s5
	v_and_b32_e32 v84, 31, v82
	global_load_lds_dwordx4 v[2:3], off
	v_lshrrev_b32_e32 v3, 1, v82
	v_lshrrev_b32_e32 v2, 5, v82
	v_and_or_b32 v95, v3, 64, v84
	v_bfe_u32 v3, v82, 1, 3
	v_bfe_u32 v94, v82, 5, 1
	v_bitop3_b32 v2, v2, v3, 1 bitop3:0x6c
	v_lshlrev_b32_e32 v96, 4, v2
	v_bitop3_b32 v2, v94, v3, 2 bitop3:0x36
	v_lshlrev_b32_e32 v99, 4, v2
	v_bitop3_b32 v2, v94, v3, 4 bitop3:0x36
	v_lshlrev_b32_e32 v100, 4, v2
	v_bitop3_b32 v2, v94, v3, 6 bitop3:0x36
	v_lshlrev_b32_e32 v4, 7, v82
	v_lshlrev_b32_e32 v101, 4, v2
	v_bitop3_b32 v2, v9, 7, v82 bitop3:0x48
	v_and_b32_e32 v4, 0x2f80, v4
	v_lshlrev_b32_e32 v2, 4, v2
	v_mov_b32_e32 v3, v1
	v_mov_b32_e32 v6, 0xc0
	v_mul_i32_i24_e32 v83, 0x11000, v8
	s_waitcnt vmcnt(0)
	v_add_u32_e32 v98, v85, v4
	v_lshl_or_b32 v4, s41, 7, v2
	v_mov_b32_e32 v5, v1
	v_mad_u64_u32 v[6:7], s[52:53], s41, v6, v[2:3]
	v_lshl_add_u64 v[8:9], s[2:3], 0, v[2:3]
	v_mov_b32_e32 v16, v1
	v_mov_b32_e32 v17, v1
	v_lshl_add_u64 v[66:67], s[20:21], 0, v[4:5]
	v_lshl_add_u64 v[68:69], s[20:21], 0, v[6:7]
	v_lshl_add_u64 v[70:71], s[20:21], 0, v[8:9]
	v_lshl_add_u64 v[72:73], s[20:21], 0, v[2:3]
	v_lshl_add_u64 v[74:75], s[18:19], 0, v[4:5]
	v_lshl_add_u64 v[76:77], s[18:19], 0, v[6:7]
	v_lshl_add_u64 v[78:79], s[18:19], 0, v[8:9]
	v_lshl_add_u64 v[80:81], s[18:19], 0, v[2:3]
	v_mov_b32_e32 v2, v1
	v_mov_b32_e32 v4, v1
	v_mov_b32_e32 v6, v1
	v_mov_b32_e32 v7, v1
	v_mov_b32_e32 v8, v1
	v_mov_b32_e32 v9, v1
	v_mov_b32_e32 v10, v1
	v_mov_b32_e32 v11, v1
	v_mov_b32_e32 v12, v1
	v_mov_b32_e32 v13, v1
	v_mov_b32_e32 v14, v1
	v_mov_b32_e32 v15, v1
	s_waitcnt vmcnt(0)
	v_mov_b64_e32 v[32:33], v[16:17]
	v_mov_b64_e32 v[48:49], v[16:17]
	v_mov_b64_e32 v[64:65], v[16:17]
	s_lshr_b32 s5, s41, 6
	v_lshl_add_u32 v97, v95, 7, v85
	s_mov_b32 s35, 2
	v_mov_b64_e32 v[30:31], v[14:15]
	v_mov_b64_e32 v[28:29], v[12:13]
	v_mov_b64_e32 v[26:27], v[10:11]
	v_mov_b64_e32 v[24:25], v[8:9]
	v_mov_b64_e32 v[22:23], v[6:7]
	v_mov_b64_e32 v[20:21], v[4:5]
	v_mov_b64_e32 v[18:19], v[2:3]
	v_mov_b64_e32 v[46:47], v[14:15]
	v_mov_b64_e32 v[44:45], v[12:13]
	v_mov_b64_e32 v[42:43], v[10:11]
	v_mov_b64_e32 v[40:41], v[8:9]
	v_mov_b64_e32 v[38:39], v[6:7]
	v_mov_b64_e32 v[36:37], v[4:5]
	v_mov_b64_e32 v[34:35], v[2:3]
	v_mov_b64_e32 v[62:63], v[14:15]
	v_mov_b64_e32 v[60:61], v[12:13]
	v_mov_b64_e32 v[58:59], v[10:11]
	v_mov_b64_e32 v[56:57], v[8:9]
	v_mov_b64_e32 v[54:55], v[6:7]
	v_mov_b64_e32 v[52:53], v[4:5]
	v_mov_b64_e32 v[50:51], v[2:3]
	s_mov_b64 s[52:53], 0x180
	s_cmp_lt_u32 s5, 2
	s_cbranch_scc1 .Ldl_pro_skip
	v_add_u32_e32 v250, 0x8000, v86
	v_lshl_add_u64 v[248:249], v[80:81], 0, v[0:1]
	v_readfirstlane_b32 s48, v250
	v_lshl_add_u64 v[248:249], v[248:249], 0, s[28:29]
	s_mov_b32 m0, s48
	s_nop 0
	global_load_lds_dwordx4 v[248:249], off
	v_add_u32_e32 v250, 0xc000, v86
	v_lshl_add_u64 v[248:249], v[72:73], 0, v[0:1]
	v_readfirstlane_b32 s48, v250
	v_lshl_add_u64 v[248:249], v[248:249], 0, s[28:29]
	s_mov_b32 m0, s48
	s_nop 0
	global_load_lds_dwordx4 v[248:249], off
	v_add_u32_e32 v250, 0x9000, v86
	v_lshl_add_u64 v[248:249], v[78:79], 0, v[0:1]
	v_readfirstlane_b32 s48, v250
	v_lshl_add_u64 v[248:249], v[248:249], 0, s[28:29]
	s_mov_b32 m0, s48
	s_nop 0
	global_load_lds_dwordx4 v[248:249], off
	v_add_u32_e32 v250, 0xd000, v86
	v_lshl_add_u64 v[248:249], v[70:71], 0, v[0:1]
	v_readfirstlane_b32 s48, v250
	v_lshl_add_u64 v[248:249], v[248:249], 0, s[28:29]
	s_mov_b32 m0, s48
	s_nop 0
	global_load_lds_dwordx4 v[248:249], off
	v_add_u32_e32 v250, 0xa000, v86
	v_lshl_add_u64 v[248:249], v[74:75], 0, v[0:1]
	v_readfirstlane_b32 s48, v250
	v_lshl_add_u64 v[248:249], v[248:249], 0, s[28:29]
	s_mov_b32 m0, s48
	s_nop 0
	global_load_lds_dwordx4 v[248:249], off
	v_add_u32_e32 v250, 0xe000, v86
	v_lshl_add_u64 v[248:249], v[66:67], 0, v[0:1]
	v_readfirstlane_b32 s48, v250
	v_lshl_add_u64 v[248:249], v[248:249], 0, s[28:29]
	s_mov_b32 m0, s48
	s_nop 0
	global_load_lds_dwordx4 v[248:249], off
	v_add_u32_e32 v250, 0xb000, v86
	v_lshl_add_u64 v[248:249], v[76:77], 0, v[0:1]
	v_readfirstlane_b32 s48, v250
	v_lshl_add_u64 v[248:249], v[248:249], 0, s[28:29]
	s_mov_b32 m0, s48
	s_nop 0
	global_load_lds_dwordx4 v[248:249], off
	v_add_u32_e32 v250, 0xf000, v86
	v_lshl_add_u64 v[248:249], v[68:69], 0, v[0:1]
	v_readfirstlane_b32 s48, v250
	v_lshl_add_u64 v[248:249], v[248:249], 0, s[28:29]
	s_mov_b32 m0, s48
	s_nop 0
	global_load_lds_dwordx4 v[248:249], off
	s_waitcnt vmcnt(0)

; #define G_WAIT() { asm volatile("s_waitcnt vmcnt(0)" ::: "memory"); __syncthreads(); }
;     ...
;   G_DMA(0, 0);
;   G_WAIT();
;   for (int kt = 0; kt < nk; kt += 2) {
;     if (kt + 1 < nk) G_DMA(1, kt + 1);
;     G_COMPUTE(0);
;     G_WAIT();
;     if (kt + 1 < nk) {
;       if (kt + 2 < nk) G_DMA(0, kt + 2);
;       G_COMPUTE(1);
;       G_WAIT();
.LBB0_168:
	v_add_u32_e32 v160, v98, v96
	v_add_u32_e32 v192, v97, v96
	v_add_u32_e32 v161, v98, v99
	v_add_u32_e32 v193, v97, v99
	v_add_u32_e32 v190, v98, v100
	v_add_u32_e32 v194, v97, v100
	v_add_u32_e32 v191, v98, v101
	v_add_u32_e32 v195, v97, v101
	ds_read_b128 v[128:131], v160 offset:16384
	ds_read_b128 v[132:135], v160 offset:20480
	ds_read_b128 v[136:139], v192 offset:0
	ds_read_b128 v[140:143], v192 offset:4096
	ds_read_b128 v[144:147], v161 offset:16384
	ds_read_b128 v[148:151], v161 offset:20480
	ds_read_b128 v[152:155], v193 offset:0
	ds_read_b128 v[156:159], v193 offset:4096
	ds_read_b128 v[216:219], v190 offset:16384
	ds_read_b128 v[220:223], v190 offset:20480
	ds_read_b128 v[224:227], v194 offset:0
	ds_read_b128 v[228:231], v194 offset:4096
	ds_read_b128 v[232:235], v191 offset:16384
	ds_read_b128 v[236:239], v191 offset:20480
	ds_read_b128 v[240:243], v195 offset:0
	ds_read_b128 v[244:247], v195 offset:4096
	s_waitcnt lgkmcnt(0)
	s_barrier
	s_cmp_lt_u32 s35, s5
	s_cbranch_scc0 .Ldl_s0_nodma
	v_add_u32_e32 v250, 0x0, v86
	v_lshl_add_u64 v[248:249], v[80:81], 0, v[0:1]
	v_readfirstlane_b32 s48, v250
	v_lshl_add_u64 v[248:249], v[248:249], 0, s[22:23]
	s_mov_b32 m0, s48
	s_nop 0
	global_load_lds_dwordx4 v[248:249], off
	v_add_u32_e32 v250, 0x4000, v86
	v_lshl_add_u64 v[248:249], v[72:73], 0, v[0:1]
	v_readfirstlane_b32 s48, v250
	v_lshl_add_u64 v[248:249], v[248:249], 0, s[22:23]
	s_mov_b32 m0, s48
	s_nop 0
	global_load_lds_dwordx4 v[248:249], off
	v_add_u32_e32 v250, 0x1000, v86
	v_lshl_add_u64 v[248:249], v[78:79], 0, v[0:1]
	v_readfirstlane_b32 s48, v250
	v_lshl_add_u64 v[248:249], v[248:249], 0, s[22:23]
	s_mov_b32 m0, s48
	s_nop 0
	global_load_lds_dwordx4 v[248:249], off
	v_add_u32_e32 v250, 0x5000, v86
	v_lshl_add_u64 v[248:249], v[70:71], 0, v[0:1]
	v_readfirstlane_b32 s48, v250
	v_lshl_add_u64 v[248:249], v[248:249], 0, s[22:23]
	s_mov_b32 m0, s48
	s_nop 0
	global_load_lds_dwordx4 v[248:249], off
	v_add_u32_e32 v250, 0x2000, v86
	v_lshl_add_u64 v[248:249], v[74:75], 0, v[0:1]
	v_readfirstlane_b32 s48, v250
	v_lshl_add_u64 v[248:249], v[248:249], 0, s[22:23]
	s_mov_b32 m0, s48
	s_nop 0
	global_load_lds_dwordx4 v[248:249], off
	v_add_u32_e32 v250, 0x6000, v86
	v_lshl_add_u64 v[248:249], v[66:67], 0, v[0:1]
	v_readfirstlane_b32 s48, v250
	v_lshl_add_u64 v[248:249], v[248:249], 0, s[22:23]
	s_mov_b32 m0, s48
	s_nop 0
	global_load_lds_dwordx4 v[248:249], off
	v_add_u32_e32 v250, 0x3000, v86
	v_lshl_add_u64 v[248:249], v[76:77], 0, v[0:1]
	v_readfirstlane_b32 s48, v250
	v_lshl_add_u64 v[248:249], v[248:249], 0, s[22:23]
	s_mov_b32 m0, s48
	s_nop 0
	global_load_lds_dwordx4 v[248:249], off
	v_add_u32_e32 v250, 0x7000, v86
	v_lshl_add_u64 v[248:249], v[68:69], 0, v[0:1]
	v_readfirstlane_b32 s48, v250
	v_lshl_add_u64 v[248:249], v[248:249], 0, s[22:23]
	s_mov_b32 m0, s48
	s_nop 0
	global_load_lds_dwordx4 v[248:249], off
	v_mfma_f32_32x32x16_bf16 v[50:65], v[128:131], v[136:139], v[50:65]
	v_mfma_f32_32x32x16_bf16 v[34:49], v[132:135], v[136:139], v[34:49]
	v_mfma_f32_32x32x16_bf16 v[18:33], v[128:131], v[140:143], v[18:33]
	v_mfma_f32_32x32x16_bf16 v[2:17], v[132:135], v[140:143], v[2:17]
	v_mfma_f32_32x32x16_bf16 v[50:65], v[144:147], v[152:155], v[50:65]
	v_mfma_f32_32x32x16_bf16 v[34:49], v[148:151], v[152:155], v[34:49]
	v_mfma_f32_32x32x16_bf16 v[18:33], v[144:147], v[156:159], v[18:33]
	v_mfma_f32_32x32x16_bf16 v[2:17], v[148:151], v[156:159], v[2:17]
	v_mfma_f32_32x32x16_bf16 v[50:65], v[216:219], v[224:227], v[50:65]
	v_mfma_f32_32x32x16_bf16 v[34:49], v[220:223], v[224:227], v[34:49]
	v_mfma_f32_32x32x16_bf16 v[18:33], v[216:219], v[228:231], v[18:33]
	v_mfma_f32_32x32x16_bf16 v[2:17], v[220:223], v[228:231], v[2:17]
	v_mfma_f32_32x32x16_bf16 v[50:65], v[232:235], v[240:243], v[50:65]
	v_mfma_f32_32x32x16_bf16 v[34:49], v[236:239], v[240:243], v[34:49]
	v_mfma_f32_32x32x16_bf16 v[18:33], v[232:235], v[244:247], v[18:33]
	v_mfma_f32_32x32x16_bf16 v[2:17], v[236:239], v[244:247], v[2:17]
	s_waitcnt vmcnt(8)
	s_barrier
	s_branch .Ldl_s1
.Ldl_s0_nodma:
	v_mfma_f32_32x32x16_bf16 v[50:65], v[128:131], v[136:139], v[50:65]
	v_mfma_f32_32x32x16_bf16 v[34:49], v[132:135], v[136:139], v[34:49]
	v_mfma_f32_32x32x16_bf16 v[18:33], v[128:131], v[140:143], v[18:33]
	v_mfma_f32_32x32x16_bf16 v[2:17], v[132:135], v[140:143], v[2:17]
	v_mfma_f32_32x32x16_bf16 v[50:65], v[144:147], v[152:155], v[50:65]
	v_mfma_f32_32x32x16_bf16 v[34:49], v[148:151], v[152:155], v[34:49]
	v_mfma_f32_32x32x16_bf16 v[18:33], v[144:147], v[156:159], v[18:33]
	v_mfma_f32_32x32x16_bf16 v[2:17], v[148:151], v[156:159], v[2:17]
	v_mfma_f32_32x32x16_bf16 v[50:65], v[216:219], v[224:227], v[50:65]
	v_mfma_f32_32x32x16_bf16 v[34:49], v[220:223], v[224:227], v[34:49]
	v_mfma_f32_32x32x16_bf16 v[18:33], v[216:219], v[228:231], v[18:33]
	v_mfma_f32_32x32x16_bf16 v[2:17], v[220:223], v[228:231], v[2:17]
	v_mfma_f32_32x32x16_bf16 v[50:65], v[232:235], v[240:243], v[50:65]
	v_mfma_f32_32x32x16_bf16 v[34:49], v[236:239], v[240:243], v[34:49]
	v_mfma_f32_32x32x16_bf16 v[18:33], v[232:235], v[244:247], v[18:33]
	v_mfma_f32_32x32x16_bf16 v[2:17], v[236:239], v[244:247], v[2:17]
	s_add_i32 s48, s35, -1
	s_cmp_lt_u32 s48, s5
	s_cbranch_scc0 .Ldl_exit
	s_waitcnt vmcnt(0)
	s_barrier
; #define G_WAIT() { asm volatile("s_waitcnt vmcnt(0)" ::: "memory"); __syncthreads(); }
;     ...
;   G_DMA(0, 0);
;   G_WAIT();
;   for (int kt = 0; kt < nk; kt += 2) {
;     if (kt + 1 < nk) G_DMA(1, kt + 1);
;     G_COMPUTE(0);
;     G_WAIT();
;     if (kt + 1 < nk) {
;       if (kt + 2 < nk) G_DMA(0, kt + 2);
;       G_COMPUTE(1);
;       G_WAIT();
;     }
;   }
.Ldl_s1:
	ds_read_b128 v[128:131], v160 offset:49152
	ds_read_b128 v[132:135], v160 offset:53248
	ds_read_b128 v[136:139], v192 offset:32768
	ds_read_b128 v[140:143], v192 offset:36864
	ds_read_b128 v[144:147], v161 offset:49152
	ds_read_b128 v[148:151], v161 offset:53248
	ds_read_b128 v[152:155], v193 offset:32768
	ds_read_b128 v[156:159], v193 offset:36864
	ds_read_b128 v[216:219], v190 offset:49152
	ds_read_b128 v[220:223], v190 offset:53248
	ds_read_b128 v[224:227], v194 offset:32768
	ds_read_b128 v[228:231], v194 offset:36864
	ds_read_b128 v[232:235], v191 offset:49152
	ds_read_b128 v[236:239], v191 offset:53248
	ds_read_b128 v[240:243], v195 offset:32768
	ds_read_b128 v[244:247], v195 offset:36864
	s_waitcnt lgkmcnt(0)
	s_barrier
	s_add_i32 s48, s35, 1
	s_cmp_lt_u32 s48, s5
	s_cbranch_scc0 .Ldl_s1_nodma
	v_add_u32_e32 v250, 0x8000, v86
	v_lshl_add_u64 v[248:249], v[80:81], 0, v[0:1]
	v_readfirstlane_b32 s48, v250
	v_lshl_add_u64 v[248:249], v[248:249], 0, s[52:53]
	s_mov_b32 m0, s48
	s_nop 0
	global_load_lds_dwordx4 v[248:249], off
	v_add_u32_e32 v250, 0xc000, v86
	v_lshl_add_u64 v[248:249], v[72:73], 0, v[0:1]
	v_readfirstlane_b32 s48, v250
	v_lshl_add_u64 v[248:249], v[248:249], 0, s[52:53]
	s_mov_b32 m0, s48
	s_nop 0
	global_load_lds_dwordx4 v[248:249], off
	v_add_u32_e32 v250, 0x9000, v86
	v_lshl_add_u64 v[248:249], v[78:79], 0, v[0:1]
	v_readfirstlane_b32 s48, v250
	v_lshl_add_u64 v[248:249], v[248:249], 0, s[52:53]
	s_mov_b32 m0, s48
	s_nop 0
	global_load_lds_dwordx4 v[248:249], off
	v_add_u32_e32 v250, 0xd000, v86
	v_lshl_add_u64 v[248:249], v[70:71], 0, v[0:1]
	v_readfirstlane_b32 s48, v250
	v_lshl_add_u64 v[248:249], v[248:249], 0, s[52:53]
	s_mov_b32 m0, s48
	s_nop 0
	global_load_lds_dwordx4 v[248:249], off
	v_add_u32_e32 v250, 0xa000, v86
	v_lshl_add_u64 v[248:249], v[74:75], 0, v[0:1]
	v_readfirstlane_b32 s48, v250
	v_lshl_add_u64 v[248:249], v[248:249], 0, s[52:53]
	s_mov_b32 m0, s48
	s_nop 0
	global_load_lds_dwordx4 v[248:249], off
	v_add_u32_e32 v250, 0xe000, v86
	v_lshl_add_u64 v[248:249], v[66:67], 0, v[0:1]
	v_readfirstlane_b32 s48, v250
	v_lshl_add_u64 v[248:249], v[248:249], 0, s[52:53]
	s_mov_b32 m0, s48
	s_nop 0
	global_load_lds_dwordx4 v[248:249], off
	v_add_u32_e32 v250, 0xb000, v86
	v_lshl_add_u64 v[248:249], v[76:77], 0, v[0:1]
	v_readfirstlane_b32 s48, v250
	v_lshl_add_u64 v[248:249], v[248:249], 0, s[52:53]
	s_mov_b32 m0, s48
	s_nop 0
	global_load_lds_dwordx4 v[248:249], off
	v_add_u32_e32 v250, 0xf000, v86
	v_lshl_add_u64 v[248:249], v[68:69], 0, v[0:1]
	v_readfirstlane_b32 s48, v250
	v_lshl_add_u64 v[248:249], v[248:249], 0, s[52:53]
	s_mov_b32 m0, s48
	s_nop 0
	global_load_lds_dwordx4 v[248:249], off
	v_mfma_f32_32x32x16_bf16 v[50:65], v[128:131], v[136:139], v[50:65]
	v_mfma_f32_32x32x16_bf16 v[34:49], v[132:135], v[136:139], v[34:49]
	v_mfma_f32_32x32x16_bf16 v[18:33], v[128:131], v[140:143], v[18:33]
	v_mfma_f32_32x32x16_bf16 v[2:17], v[132:135], v[140:143], v[2:17]
	v_mfma_f32_32x32x16_bf16 v[50:65], v[144:147], v[152:155], v[50:65]
	v_mfma_f32_32x32x16_bf16 v[34:49], v[148:151], v[152:155], v[34:49]
	v_mfma_f32_32x32x16_bf16 v[18:33], v[144:147], v[156:159], v[18:33]
	v_mfma_f32_32x32x16_bf16 v[2:17], v[148:151], v[156:159], v[2:17]
	v_mfma_f32_32x32x16_bf16 v[50:65], v[216:219], v[224:227], v[50:65]
	v_mfma_f32_32x32x16_bf16 v[34:49], v[220:223], v[224:227], v[34:49]
	v_mfma_f32_32x32x16_bf16 v[18:33], v[216:219], v[228:231], v[18:33]
	v_mfma_f32_32x32x16_bf16 v[2:17], v[220:223], v[228:231], v[2:17]
	v_mfma_f32_32x32x16_bf16 v[50:65], v[232:235], v[240:243], v[50:65]
	v_mfma_f32_32x32x16_bf16 v[34:49], v[236:239], v[240:243], v[34:49]
	v_mfma_f32_32x32x16_bf16 v[18:33], v[232:235], v[244:247], v[18:33]
	v_mfma_f32_32x32x16_bf16 v[2:17], v[236:239], v[244:247], v[2:17]
	s_waitcnt vmcnt(8)
	s_barrier
	s_branch .Ldl_next
.Ldl_s1_nodma:
	v_mfma_f32_32x32x16_bf16 v[50:65], v[128:131], v[136:139], v[50:65]
	v_mfma_f32_32x32x16_bf16 v[34:49], v[132:135], v[136:139], v[34:49]
	v_mfma_f32_32x32x16_bf16 v[18:33], v[128:131], v[140:143], v[18:33]
	v_mfma_f32_32x32x16_bf16 v[2:17], v[132:135], v[140:143], v[2:17]
	v_mfma_f32_32x32x16_bf16 v[50:65], v[144:147], v[152:155], v[50:65]
	v_mfma_f32_32x32x16_bf16 v[34:49], v[148:151], v[152:155], v[34:49]
	v_mfma_f32_32x32x16_bf16 v[18:33], v[144:147], v[156:159], v[18:33]
	v_mfma_f32_32x32x16_bf16 v[2:17], v[148:151], v[156:159], v[2:17]
	v_mfma_f32_32x32x16_bf16 v[50:65], v[216:219], v[224:227], v[50:65]
	v_mfma_f32_32x32x16_bf16 v[34:49], v[220:223], v[224:227], v[34:49]
	v_mfma_f32_32x32x16_bf16 v[18:33], v[216:219], v[228:231], v[18:33]
	v_mfma_f32_32x32x16_bf16 v[2:17], v[220:223], v[228:231], v[2:17]
	v_mfma_f32_32x32x16_bf16 v[50:65], v[232:235], v[240:243], v[50:65]
	v_mfma_f32_32x32x16_bf16 v[34:49], v[236:239], v[240:243], v[34:49]
	v_mfma_f32_32x32x16_bf16 v[18:33], v[232:235], v[244:247], v[18:33]
	v_mfma_f32_32x32x16_bf16 v[2:17], v[236:239], v[244:247], v[2:17]
	s_cmp_lt_u32 s35, s5
	s_cbranch_scc0 .Ldl_exit
	s_waitcnt vmcnt(0)
	s_barrier
.Ldl_next:
	v_lshl_add_u64 v[66:67], v[66:67], 0, s[22:23]
	v_lshl_add_u64 v[68:69], v[68:69], 0, s[22:23]
	v_lshl_add_u64 v[70:71], v[70:71], 0, s[22:23]
	v_lshl_add_u64 v[72:73], v[72:73], 0, s[22:23]
	v_lshl_add_u64 v[74:75], v[74:75], 0, s[22:23]
	v_lshl_add_u64 v[76:77], v[76:77], 0, s[22:23]
	v_lshl_add_u64 v[78:79], v[78:79], 0, s[22:23]
	v_lshl_add_u64 v[80:81], v[80:81], 0, s[22:23]
	s_add_i32 s35, s35, 2
	s_branch .LBB0_168
.Ldl_exit:
	v_lshl_add_u64 v[66:67], v[66:67], 0, s[22:23]
	v_lshl_add_u64 v[68:69], v[68:69], 0, s[22:23]
	v_lshl_add_u64 v[70:71], v[70:71], 0, s[22:23]
	v_lshl_add_u64 v[72:73], v[72:73], 0, s[22:23]
	v_lshl_add_u64 v[74:75], v[74:75], 0, s[22:23]
	v_lshl_add_u64 v[76:77], v[76:77], 0, s[22:23]
	v_lshl_add_u64 v[78:79], v[78:79], 0, s[22:23]
	v_lshl_add_u64 v[80:81], v[80:81], 0, s[22:23]
	s_branch .LBB0_176
